# attention tile loop: block-2 accumulator takes -max as MFMA C operand (no copies); block-1 exps issued in the gaps of block 2's MFMA chain
# baseline (speedup 1.0000x reference)
; DI float xmax32(float s) { const auto r = __builtin_amdgcn_permlane32_swap(__float_as_uint(s), __float_as_uint(s), false, false); return fmaxf(__uint_as_float(r[0]), __uint_as_float(r[1])); }
; DI int crow(int r, int hi) { return (r & 3) + 8 * (r >> 2) + 4 * hi; }
; #define SB() __builtin_amdgcn_sched_barrier(0)
; #define LGKM(n) asm volatile("s_waitcnt lgkmcnt(" #n ")" ::: "memory")
;     ...
;             SB(); LDH(fa, 0, 0); SB();
; #pragma unroll
;             for (int bb = 0; bb < 2 * NBH; ++bb) {
;                 const int nb = bb + 1;
;                 if (nb < 2 * NBH) { if (nb & 1) LDH(fb, nb / NBH, nb % NBH); else LDH(fa, nb / NBH, nb % NBH); }
;                 SB();
;                 if (bb < NBH) { if (bb & 1) MMH(s0, fb, bb % NBH); else MMH(s0, fa, bb % NBH); }
;                 else          { if (bb & 1) MMH(s1, fb, bb % NBH); else MMH(s1, fa, bb % NBH); }
;                 if (bb == NBH) {
;                     if (CAUSAL && (64 * t + 31 > qmin)) {
; #pragma unroll
;                         for (int i = 0; i < 16; ++i) { const int kv = 64 * t + crow(i, h); if (kv > qpos) s0[i] = -INFINITY; } }
;                     float m0b = fmaxf(fmaxf(s0[3], s0[4]), s0[5]); m0 = fmaxf(fmaxf(s0[0], s0[1]), s0[2]);
; #pragma unroll
;                     for (int i = 6; i < 15; i += 3) { m0 = fmaxf(fmaxf(m0, s0[i]), s0[i + 1]); m0b = fmaxf(m0b, s0[i + 2]); }
;                     m0 = fmaxf(fmaxf(m0, m0b), s0[15]);
; #pragma unroll
;                     for (int i = 0; i < 16; ++i) { s0[i] = __builtin_amdgcn_exp2f(s0[i]); ps += s0[i]; }
;                     pf[0] = pack8(s0, 0); pf[1] = pack8(s0, 8); }
;                 SB(); }
;             LDV(la, ha, 0); SB(); LGKM(0); SB();
;             MMV(la, ha, 0); SB(); LDV(la, ha, 1); LGKM(0); SB(); MMV(la, ha, 1); SB(); LDV(la, ha, 2); SB();
;             if (CAUSAL && (64 * t + 63 > qmin)) {
; #pragma unroll
;                 for (int i = 0; i < 16; ++i) { const int kv = 64 * t + 32 + crow(i, h); if (kv > qpos) s1[i] = -INFINITY; } }
;             float m1 = fmaxf(fmaxf(s1[0], s1[1]), s1[2]), m1b = fmaxf(fmaxf(s1[3], s1[4]), s1[5]);
; #pragma unroll
;             for (int i = 6; i < 15; i += 3) { m1 = fmaxf(fmaxf(m1, s1[i]), s1[i + 1]); m1b = fmaxf(m1b, s1[i + 2]); }
;             m1 = fmaxf(fmaxf(m1, m1b), s1[15]);
;             const float rm = xmax32(fmaxf(m0, m1));
.LBB0_604:
	s_mul_i32 s8, s17, 0x9400
	s_add_i32 s8, s8, 0
	v_add3_u32 v164, s8, v1, v162
	v_add3_u32 v98, s8, v163, v166
	ds_read_b128 v[82:85], v164
	ds_read_b128 v[86:89], v164 offset:32
	ds_read_b128 v[90:93], v164 offset:64
	ds_read_b128 v[94:97], v164 offset:96
	s_movk_i32 s8, 0x4400
	v_add3_u32 v169, v98, v167, s8
	ds_read_b128 v[146:149], v164 offset:128
	ds_read_b128 v[170:173], v164 offset:160
	ds_read_b128 v[174:177], v164 offset:192
	ds_read_b128 v[180:183], v164 offset:224
	s_waitcnt lgkmcnt(0)
	v_mfma_f32_32x32x16_bf16 v[98:113], v[82:85], v[114:117], v[66:81]
	v_mfma_f32_32x32x16_bf16 v[98:113], v[86:89], v[118:121], v[98:113]
	v_mfma_f32_32x32x16_bf16 v[98:113], v[90:93], v[122:125], v[98:113]
	v_mfma_f32_32x32x16_bf16 v[98:113], v[94:97], v[126:129], v[98:113]
	ds_read_b128 v[184:187], v164 offset:8704
	ds_read_b128 v[188:191], v164 offset:8736
	ds_read_b128 v[192:195], v164 offset:8768
	ds_read_b128 v[196:199], v164 offset:8800
	v_mfma_f32_32x32x16_bf16 v[98:113], v[146:149], v[130:133], v[98:113]
	v_mfma_f32_32x32x16_bf16 v[98:113], v[170:173], v[134:137], v[98:113]
	v_mfma_f32_32x32x16_bf16 v[98:113], v[174:177], v[138:141], v[98:113]
	v_mfma_f32_32x32x16_bf16 v[98:113], v[180:183], v[142:145], v[98:113]
	ds_read_b128 v[146:149], v164 offset:8832
	ds_read_b128 v[170:173], v164 offset:8864
	ds_read_b128 v[174:177], v164 offset:8896
	ds_read_b128 v[180:183], v164 offset:8928
	s_nop 7
	v_max_f32_e32 v164, v102, v102
	v_max_f32_e32 v200, v101, v101
	s_waitcnt lgkmcnt(0)
	v_mfma_f32_32x32x16_bf16 v[82:97], v[184:187], v[114:117], v[66:81]
	v_max_f32_e32 v201, v98, v98
	v_exp_f32_e32 v98, v98
	v_max_f32_e32 v164, v200, v164
	v_max_f32_e32 v200, v99, v99
	v_exp_f32_e32 v99, v99
	v_exp_f32_e32 v186, v100
	v_max3_f32 v164, v164, v103, v106
	v_mfma_f32_32x32x16_bf16 v[82:97], v[188:191], v[118:121], v[82:97]
	v_exp_f32_e32 v101, v101
	v_max3_f32 v185, v164, v109, v112
	v_add_f32_e32 v164, 0, v98
	v_exp_f32_e32 v102, v102
	v_add_f32_e32 v164, v99, v164
	v_exp_f32_e32 v103, v103
	v_add_f32_e32 v164, v186, v164
	v_mfma_f32_32x32x16_bf16 v[82:97], v[192:195], v[122:125], v[82:97]
	v_exp_f32_e32 v187, v104
	v_add_f32_e32 v164, v101, v164
	v_exp_f32_e32 v188, v105
	v_add_f32_e32 v164, v102, v164
	v_exp_f32_e32 v106, v106
	v_add_f32_e32 v164, v103, v164
	v_exp_f32_e32 v189, v107
	v_add_f32_e32 v164, v187, v164
	v_exp_f32_e32 v190, v108
	v_add_f32_e32 v164, v188, v164
	v_exp_f32_e32 v109, v109
	v_mfma_f32_32x32x16_bf16 v[82:97], v[196:199], v[126:129], v[82:97]
	v_add_f32_e32 v164, v106, v164
	v_exp_f32_e32 v191, v110
	v_add_f32_e32 v164, v189, v164
	v_exp_f32_e32 v192, v111
	v_add_f32_e32 v164, v190, v164
	v_exp_f32_e32 v112, v112
	v_max_f32_e32 v184, v201, v200
	v_add_f32_e32 v164, v109, v164
	v_exp_f32_e32 v193, v113
	v_add_f32_e32 v164, v191, v164
	v_max3_f32 v100, v184, v100, v104
	v_add_f32_e32 v164, v192, v164
	v_max3_f32 v100, v100, v105, v107
	v_add_f32_e32 v164, v112, v164
	v_max3_f32 v100, v100, v108, v110
	v_add_f32_e32 v164, v193, v164
	v_max3_f32 v110, v100, v111, v185
	v_cvt_pk_bf16_f32 v98, v98, v99
	v_cvt_pk_bf16_f32 v99, v186, v101
	v_cvt_pk_bf16_f32 v100, v102, v103
	v_cvt_pk_bf16_f32 v101, v187, v188
	v_cvt_pk_bf16_f32 v102, v106, v189
	v_cvt_pk_bf16_f32 v103, v190, v109
	v_cvt_pk_bf16_f32 v104, v191, v192
	v_cvt_pk_bf16_f32 v105, v112, v193
	v_mfma_f32_32x32x16_bf16 v[82:97], v[146:149], v[130:133], v[82:97]
	v_mfma_f32_32x32x16_bf16 v[82:97], v[170:173], v[134:137], v[82:97]
	v_mfma_f32_32x32x16_bf16 v[82:97], v[174:177], v[138:141], v[82:97]
	v_mfma_f32_32x32x16_bf16 v[82:97], v[180:183], v[142:145], v[82:97]
	ds_read_b64_tr_b16 v[106:107], v169 offset:0
	ds_read_b64_tr_b16 v[108:109], v169 offset:2560
	ds_read_b64_tr_b16 v[146:147], v169 offset:64
	ds_read_b64_tr_b16 v[148:149], v169 offset:2624
	ds_read_b64_tr_b16 v[170:171], v169 offset:128
	ds_read_b64_tr_b16 v[172:173], v169 offset:2688
	ds_read_b64_tr_b16 v[174:175], v169 offset:192
	ds_read_b64_tr_b16 v[176:177], v169 offset:2752
	s_waitcnt lgkmcnt(0)
	s_nop 0
	v_mfma_f32_32x32x16_bf16 v[50:65], v[106:109], v[98:101], v[50:65]
	v_mfma_f32_32x32x16_bf16 v[34:49], v[146:149], v[98:101], v[34:49]
	v_mfma_f32_32x32x16_bf16 v[18:33], v[170:173], v[98:101], v[18:33]
	v_mfma_f32_32x32x16_bf16 v[2:17], v[174:177], v[98:101], v[2:17]
	ds_read_b64_tr_b16 v[98:99], v169 offset:5120
	ds_read_b64_tr_b16 v[100:101], v169 offset:7680
	ds_read_b64_tr_b16 v[106:107], v169 offset:5184
	ds_read_b64_tr_b16 v[108:109], v169 offset:7744
	ds_read_b64_tr_b16 v[146:147], v169 offset:5248
	ds_read_b64_tr_b16 v[148:149], v169 offset:7808
	ds_read_b64_tr_b16 v[170:171], v169 offset:5312
	ds_read_b64_tr_b16 v[172:173], v169 offset:7872
	s_waitcnt lgkmcnt(0)
	s_nop 0
	v_mfma_f32_32x32x16_bf16 v[50:65], v[98:101], v[102:105], v[50:65]
	v_mfma_f32_32x32x16_bf16 v[34:49], v[106:109], v[102:105], v[34:49]
	v_mfma_f32_32x32x16_bf16 v[18:33], v[146:149], v[102:105], v[18:33]
	v_mfma_f32_32x32x16_bf16 v[2:17], v[170:173], v[102:105], v[2:17]
	ds_read_b64_tr_b16 v[146:147], v169 offset:10240
	ds_read_b64_tr_b16 v[148:149], v169 offset:12800
	ds_read_b64_tr_b16 v[106:107], v169 offset:10304
	ds_read_b64_tr_b16 v[108:109], v169 offset:12864
	ds_read_b64_tr_b16 v[102:103], v169 offset:10368
	ds_read_b64_tr_b16 v[104:105], v169 offset:12928
	ds_read_b64_tr_b16 v[98:99], v169 offset:10432
	ds_read_b64_tr_b16 v[100:101], v169 offset:12992
	s_nop 1
	v_max3_f32 v111, v82, v83, v84
	v_max_f32_e32 v112, v86, v86
	v_max_f32_e32 v170, v85, v85
	v_max_f32_e32 v112, v170, v112
	v_max3_f32 v111, v111, v88, v89
	v_max3_f32 v112, v112, v87, v90
	v_max3_f32 v111, v111, v91, v92
	v_max3_f32 v111, v111, v94, v95
	v_max3_f32 v112, v112, v93, v96
	v_max3_f32 v111, v111, v112, v97
	v_max3_f32 v110, v110, v113, v111
	v_mov_b32_e32 v111, v110
	s_nop 1
	v_permlane32_swap_b32_e32 v110, v111
	v_max_f32_e32 v111, v111, v111
	v_max_f32_e32 v110, v110, v110
	s_cmp_lg_u32 s15, 0
	v_max_f32_e32 v111, v110, v111
	s_cbranch_scc0 .LBB0_618
	s_mov_b32 s8, 0x41000000
	v_cmp_lt_f32_e32 vcc, s8, v111
	s_mov_b64 s[10:11], 0
	s_mov_b64 s[8:9], 0
	s_cbranch_vccz .LBB0_607
	v_max_f32_e32 v110, v111, v111
	v_max_f32_e32 v110, 0, v110
	s_mov_b64 s[8:9], -1

; DI int crow(int r, int hi) { return (r & 3) + 8 * (r >> 2) + 4 * hi; }
; #define SB() __builtin_amdgcn_sched_barrier(0)
; #define LDH(dst, half, b2) do { _Pragma("unroll") for (int j = 0; j < HB; ++j) dst[j] = *(const LAS bf16x8*)(kb_ + (half) * 32 * KP + ((b2) * HB + j) * 32); } while (0)
; #define MMH(S, src, b2) do { _Pragma("unroll") for (int j = 0; j < HB; ++j) { if ((b2) == 0 && j == 0) S = MFMA32(src[0], qf[0], negm); else S = MFMA32(src[j], qf[(b2) * HB + j], S); } } while (0)
;     ...
;             SB(); LDH(fa, 0, 0); SB();
; #pragma unroll
;             for (int bb = 0; bb < 2 * NBH; ++bb) {
;                 const int nb = bb + 1;
;                 if (nb < 2 * NBH) { if (nb & 1) LDH(fb, nb / NBH, nb % NBH); else LDH(fa, nb / NBH, nb % NBH); }
;                 SB();
;                 if (bb < NBH) { if (bb & 1) MMH(s0, fb, bb % NBH); else MMH(s0, fa, bb % NBH); }
;                 else          { if (bb & 1) MMH(s1, fb, bb % NBH); else MMH(s1, fa, bb % NBH); }
;                 if (bb == NBH) {
;                     if (CAUSAL && (64 * t + 31 > qmin)) {
; #pragma unroll
;                         for (int i = 0; i < 16; ++i) { const int kv = 64 * t + crow(i, h); if (kv > qpos) s0[i] = -INFINITY; } }
.LBB0_875:
	s_mul_i32 s24, s62, 0xb400
	s_add_i32 s24, s24, 0
	v_add_u32_e32 v80, s24, v191
	v_add_u32_e32 v168, v80, v190
	ds_read_b128 v[80:83], v168
	ds_read_b128 v[84:87], v168 offset:32
	ds_read_b128 v[88:91], v168 offset:64
	ds_read_b128 v[92:95], v168 offset:96
	s_add_i32 s25, s58, 31
	s_cmp_le_i32 s25, s54
	s_waitcnt lgkmcnt(0)
	v_mfma_f32_32x32x16_bf16 v[96:111], v[80:83], v[112:115], v[64:79]
	v_mfma_f32_32x32x16_bf16 v[96:111], v[84:87], v[116:119], v[96:111]
	ds_read_b128 v[80:83], v168 offset:128
	ds_read_b128 v[84:87], v168 offset:160
	v_mfma_f32_32x32x16_bf16 v[96:111], v[88:91], v[120:123], v[96:111]
	v_mfma_f32_32x32x16_bf16 v[96:111], v[92:95], v[124:127], v[96:111]
	ds_read_b128 v[88:91], v168 offset:192
	ds_read_b128 v[92:95], v168 offset:224
	s_waitcnt lgkmcnt(0)
	v_mfma_f32_32x32x16_bf16 v[96:111], v[80:83], v[128:131], v[96:111]
	v_mfma_f32_32x32x16_bf16 v[96:111], v[84:87], v[132:135], v[96:111]
	ds_read_b128 v[80:83], v168 offset:256
	ds_read_b128 v[84:87], v168 offset:288
	v_mfma_f32_32x32x16_bf16 v[96:111], v[88:91], v[136:139], v[96:111]
	v_mfma_f32_32x32x16_bf16 v[96:111], v[92:95], v[140:143], v[96:111]
	ds_read_b128 v[88:91], v168 offset:320
	ds_read_b128 v[92:95], v168 offset:352
	s_waitcnt lgkmcnt(0)
	v_mfma_f32_32x32x16_bf16 v[96:111], v[80:83], v[144:147], v[96:111]
	v_mfma_f32_32x32x16_bf16 v[96:111], v[84:87], v[148:151], v[96:111]
	ds_read_b128 v[170:173], v168 offset:12800
	ds_read_b128 v[216:219], v168 offset:12832
	v_mfma_f32_32x32x16_bf16 v[96:111], v[88:91], v[152:155], v[96:111]
	v_mfma_f32_32x32x16_bf16 v[96:111], v[92:95], v[156:159], v[96:111]
	ds_read_b128 v[164:167], v168 offset:12864
	ds_read_b128 v[160:163], v168 offset:12896
	s_nop 7
	v_add_u32_e32 v204, s58, v210
	s_waitcnt lgkmcnt(0)
	v_mfma_f32_32x32x16_bf16 v[80:95], v[170:173], v[112:115], v[64:79]
	v_mfma_f32_32x32x16_bf16 v[80:95], v[216:219], v[116:119], v[80:95]
	s_cbranch_scc1 .LBB0_877
	v_cmp_lt_i32_e32 vcc, v204, v209
	v_add_u32_e32 v169, 2, v204
	s_nop 0
	v_cndmask_b32_e32 v97, v208, v97, vcc
	v_cmp_le_i32_e32 vcc, v204, v209
	s_nop 1
	v_cndmask_b32_e32 v96, v208, v96, vcc
	v_cmp_le_i32_e32 vcc, v169, v209
	v_add_u32_e32 v169, 3, v204
	s_nop 0
	v_cndmask_b32_e32 v98, v208, v98, vcc
	v_cmp_le_i32_e32 vcc, v169, v209
	v_add_u32_e32 v169, 8, v204
	s_nop 0
	v_cndmask_b32_e32 v99, v208, v99, vcc
	v_cmp_le_i32_e32 vcc, v169, v209
	v_add_u32_e32 v169, 9, v204
	s_nop 0
	v_cndmask_b32_e32 v100, v208, v100, vcc
	v_cmp_le_i32_e32 vcc, v169, v209
	v_add_u32_e32 v169, 10, v204
	s_nop 0
	v_cndmask_b32_e32 v101, v208, v101, vcc
	v_cmp_le_i32_e32 vcc, v169, v209
	v_add_u32_e32 v169, 11, v204
	s_nop 0
	v_cndmask_b32_e32 v102, v208, v102, vcc
	v_cmp_le_i32_e32 vcc, v169, v209
	v_add_u32_e32 v169, 16, v204
	s_nop 0
	v_cndmask_b32_e32 v103, v208, v103, vcc
	v_cmp_le_i32_e32 vcc, v169, v209
	v_add_u32_e32 v169, 17, v204
	s_nop 0
	v_cndmask_b32_e32 v104, v208, v104, vcc
	v_cmp_le_i32_e32 vcc, v169, v209
	v_add_u32_e32 v169, 18, v204
	s_nop 0
	v_cndmask_b32_e32 v105, v208, v105, vcc
	v_cmp_le_i32_e32 vcc, v169, v209
	v_add_u32_e32 v169, 19, v204
	s_nop 0
	v_cndmask_b32_e32 v106, v208, v106, vcc
	v_cmp_le_i32_e32 vcc, v169, v209
	v_add_u32_e32 v169, 24, v204
	s_nop 0
	v_cndmask_b32_e32 v107, v208, v107, vcc
	v_cmp_le_i32_e32 vcc, v169, v209
	v_add_u32_e32 v169, 25, v204
	s_nop 0
	v_cndmask_b32_e32 v108, v208, v108, vcc
	v_cmp_le_i32_e32 vcc, v169, v209
	v_add_u32_e32 v169, 26, v204
	s_nop 0
	v_cndmask_b32_e32 v109, v208, v109, vcc
	v_cmp_le_i32_e32 vcc, v169, v209
	v_add_u32_e32 v169, 27, v204
	s_nop 0
	v_cndmask_b32_e32 v110, v208, v110, vcc
	v_cmp_le_i32_e32 vcc, v169, v209
	s_nop 1
	v_cndmask_b32_e32 v111, v208, v111, vcc
; DI int crow(int r, int hi) { return (r & 3) + 8 * (r >> 2) + 4 * hi; }
; DI bf16x8 pack8(const f32x16& x, int o) { u32x4 w; w.x = cvtpk(x[o], x[o + 1]); w.y = cvtpk(x[o + 2], x[o + 3]); w.z = cvtpk(x[o + 4], x[o + 5]); w.w = cvtpk(x[o + 6], x[o + 7]); return __builtin_bit_cast(bf16x8, w); }
; #define SB() __builtin_amdgcn_sched_barrier(0)
; #define LDV(lo, hi, s) do { _Pragma("unroll") for (int d = 0; d < 4; ++d) { TRR(lo[d], (16 * (s)) * VP + d * 64); TRR(hi[d], (16 * (s) + 8) * VP + d * 64); } } while (0)
; #define MMV(lo, hi, s) do { if (ABL & 4) { _Pragma("unroll") for (int d = 0; d < 4; ++d) o[d][0] += (float)lo[d][0] + (float)hi[d][0] + (float)pf[s][d]; break; } _Pragma("unroll") for (int d = 0; d < 4; ++d) o[d] = MFMA32(((bf16x8){lo[d][0], lo[d][1], lo[d][2], lo[d][3], hi[d][0], hi[d][1], hi[d][2], hi[d][3]}), pf[s], o[d]); } while (0)
; #define LGKM(n) asm volatile("s_waitcnt lgkmcnt(" #n ")" ::: "memory")
;     ...
;                     float m0b = fmaxf(fmaxf(s0[3], s0[4]), s0[5]); m0 = fmaxf(fmaxf(s0[0], s0[1]), s0[2]);
; #pragma unroll
;                     for (int i = 6; i < 15; i += 3) { m0 = fmaxf(fmaxf(m0, s0[i]), s0[i + 1]); m0b = fmaxf(m0b, s0[i + 2]); }
;                     m0 = fmaxf(fmaxf(m0, m0b), s0[15]);
; #pragma unroll
;                     for (int i = 0; i < 16; ++i) { s0[i] = __builtin_amdgcn_exp2f(s0[i]); ps += s0[i]; }
;                     pf[0] = pack8(s0, 0); pf[1] = pack8(s0, 8); }
;                 SB(); }
;             LDV(la, ha, 0); SB(); LGKM(0); SB();
;             MMV(la, ha, 0); SB(); LDV(la, ha, 1); LGKM(0); SB(); MMV(la, ha, 1); SB(); LDV(la, ha, 2); SB();
;             if (CAUSAL && (64 * t + 63 > qmin)) {
; #pragma unroll
;                 for (int i = 0; i < 16; ++i) { const int kv = 64 * t + 32 + crow(i, h); if (kv > qpos) s1[i] = -INFINITY; } }
.LBB0_877:
	ds_read_b128 v[238:241], v168 offset:12928
	ds_read_b128 v[242:245], v168 offset:12960
	v_mfma_f32_32x32x16_bf16 v[80:95], v[164:167], v[120:123], v[80:95]
	v_exp_f32_e32 v216, v96
	v_exp_f32_e32 v217, v97
	v_mfma_f32_32x32x16_bf16 v[80:95], v[160:163], v[124:127], v[80:95]
	v_exp_f32_e32 v218, v98
	v_exp_f32_e32 v219, v99
	ds_read_b128 v[160:163], v168 offset:12992
	ds_read_b128 v[164:167], v168 offset:13024
	s_waitcnt lgkmcnt(0)
	v_mfma_f32_32x32x16_bf16 v[80:95], v[238:241], v[128:131], v[80:95]
	v_exp_f32_e32 v220, v100
	v_exp_f32_e32 v221, v101
	v_mfma_f32_32x32x16_bf16 v[80:95], v[242:245], v[132:135], v[80:95]
	v_exp_f32_e32 v222, v102
	v_exp_f32_e32 v223, v103
	ds_read_b128 v[238:241], v168 offset:13056
	ds_read_b128 v[242:245], v168 offset:13088
	v_mfma_f32_32x32x16_bf16 v[80:95], v[160:163], v[136:139], v[80:95]
	v_exp_f32_e32 v224, v104
	v_exp_f32_e32 v225, v105
	v_mfma_f32_32x32x16_bf16 v[80:95], v[164:167], v[140:143], v[80:95]
	v_exp_f32_e32 v226, v106
	v_exp_f32_e32 v227, v107
	ds_read_b128 v[160:163], v168 offset:13120
	ds_read_b128 v[164:167], v168 offset:13152
	s_waitcnt lgkmcnt(0)
	v_mfma_f32_32x32x16_bf16 v[80:95], v[238:241], v[144:147], v[80:95]
	v_exp_f32_e32 v228, v108
	v_exp_f32_e32 v229, v109
	v_mfma_f32_32x32x16_bf16 v[80:95], v[242:245], v[148:151], v[80:95]
	v_exp_f32_e32 v230, v110
	v_exp_f32_e32 v231, v111
	v_mfma_f32_32x32x16_bf16 v[80:95], v[160:163], v[152:155], v[80:95]
	v_add3_u32 v169, s24, v211, v212
	v_add3_u32 v215, v169, v213, s40
	v_cvt_pk_bf16_f32 v170, v216, v217
	v_cvt_pk_bf16_f32 v171, v218, v219
	v_cvt_pk_bf16_f32 v172, v220, v221
	v_cvt_pk_bf16_f32 v173, v222, v223
	v_mfma_f32_32x32x16_bf16 v[80:95], v[164:167], v[156:159], v[80:95]
	v_cvt_pk_bf16_f32 v234, v224, v225
	v_cvt_pk_bf16_f32 v235, v226, v227
	v_cvt_pk_bf16_f32 v236, v228, v229
	v_cvt_pk_bf16_f32 v237, v230, v231
	ds_read_b64_tr_b16 v[160:161], v215 offset:0
	ds_read_b64_tr_b16 v[162:163], v215 offset:2560
	ds_read_b64_tr_b16 v[164:165], v215 offset:64
	ds_read_b64_tr_b16 v[166:167], v215 offset:2624
	ds_read_b64_tr_b16 v[238:239], v215 offset:128
	ds_read_b64_tr_b16 v[240:241], v215 offset:2688
	ds_read_b64_tr_b16 v[242:243], v215 offset:192
	ds_read_b64_tr_b16 v[244:245], v215 offset:2752
	s_waitcnt lgkmcnt(0)
	s_nop 0
	v_mfma_f32_32x32x16_bf16 v[48:63], v[160:163], v[170:173], v[48:63]
	v_mfma_f32_32x32x16_bf16 v[32:47], v[164:167], v[170:173], v[32:47]
	v_mfma_f32_32x32x16_bf16 v[16:31], v[238:241], v[170:173], v[16:31]
	v_mfma_f32_32x32x16_bf16 v[0:15], v[242:245], v[170:173], v[0:15]
	ds_read_b64_tr_b16 v[160:161], v215 offset:5120
	ds_read_b64_tr_b16 v[162:163], v215 offset:7680
	ds_read_b64_tr_b16 v[164:165], v215 offset:5184
	ds_read_b64_tr_b16 v[166:167], v215 offset:7744
	ds_read_b64_tr_b16 v[168:169], v215 offset:5248
	ds_read_b64_tr_b16 v[170:171], v215 offset:7808
	ds_read_b64_tr_b16 v[172:173], v215 offset:5312
	ds_read_b64_tr_b16 v[174:175], v215 offset:7872
	s_waitcnt lgkmcnt(0)
	s_nop 0
	v_mfma_f32_32x32x16_bf16 v[48:63], v[160:163], v[234:237], v[48:63]
	v_mfma_f32_32x32x16_bf16 v[32:47], v[164:167], v[234:237], v[32:47]
	v_mfma_f32_32x32x16_bf16 v[16:31], v[168:171], v[234:237], v[16:31]
	v_mfma_f32_32x32x16_bf16 v[0:15], v[172:175], v[234:237], v[0:15]
	ds_read_b64_tr_b16 v[172:173], v215 offset:10240
	ds_read_b64_tr_b16 v[174:175], v215 offset:12800
	ds_read_b64_tr_b16 v[168:169], v215 offset:10304
	ds_read_b64_tr_b16 v[170:171], v215 offset:12864
	ds_read_b64_tr_b16 v[164:165], v215 offset:10368
	ds_read_b64_tr_b16 v[166:167], v215 offset:12928
	ds_read_b64_tr_b16 v[160:161], v215 offset:10432
	ds_read_b64_tr_b16 v[162:163], v215 offset:12992
	s_add_i32 s24, s58, 63
	s_cmp_le_i32 s24, s54
	s_cbranch_scc1 .LBB0_879
	v_add_u32_e32 v233, 32, v204
	v_cmp_le_i32_e32 vcc, v233, v209
	v_add_u32_e32 v233, 33, v204
	s_nop 0
	v_cndmask_b32_e32 v80, v208, v80, vcc
	v_cmp_le_i32_e32 vcc, v233, v209
	v_add_u32_e32 v233, 34, v204
	s_nop 0
	v_cndmask_b32_e32 v81, v208, v81, vcc
	v_cmp_le_i32_e32 vcc, v233, v209
	v_add_u32_e32 v233, 35, v204
	s_nop 0
	v_cndmask_b32_e32 v82, v208, v82, vcc
	v_cmp_le_i32_e32 vcc, v233, v209
	v_add_u32_e32 v233, 40, v204
	s_nop 0
	v_cndmask_b32_e32 v83, v208, v83, vcc
	v_cmp_le_i32_e32 vcc, v233, v209
	v_add_u32_e32 v233, 41, v204
	s_nop 0
	v_cndmask_b32_e32 v84, v208, v84, vcc
	v_cmp_le_i32_e32 vcc, v233, v209
	v_add_u32_e32 v233, 42, v204
	s_nop 0
	v_cndmask_b32_e32 v85, v208, v85, vcc
	v_cmp_le_i32_e32 vcc, v233, v209
	v_add_u32_e32 v233, 43, v204
	s_nop 0
	v_cndmask_b32_e32 v86, v208, v86, vcc
	v_cmp_le_i32_e32 vcc, v233, v209
	v_add_u32_e32 v233, 48, v204
	s_nop 0
	v_cndmask_b32_e32 v87, v208, v87, vcc
	v_cmp_le_i32_e32 vcc, v233, v209
	v_add_u32_e32 v233, 49, v204
	s_nop 0
	v_cndmask_b32_e32 v88, v208, v88, vcc
	v_cmp_le_i32_e32 vcc, v233, v209
	v_add_u32_e32 v233, 50, v204
	s_nop 0
	v_cndmask_b32_e32 v89, v208, v89, vcc
	v_cmp_le_i32_e32 vcc, v233, v209
	v_add_u32_e32 v233, 51, v204
	s_nop 0
	v_cndmask_b32_e32 v90, v208, v90, vcc
	v_cmp_le_i32_e32 vcc, v233, v209
	v_add_u32_e32 v233, 56, v204
	s_nop 0
	v_cndmask_b32_e32 v91, v208, v91, vcc
	v_cmp_le_i32_e32 vcc, v233, v209
	v_add_u32_e32 v233, 57, v204
	s_nop 0
	v_cndmask_b32_e32 v92, v208, v92, vcc
	v_cmp_le_i32_e32 vcc, v233, v209
	v_add_u32_e32 v233, 58, v204
	v_add_u32_e32 v204, 59, v204
	v_cndmask_b32_e32 v93, v208, v93, vcc
	v_cmp_le_i32_e32 vcc, v233, v209
	s_nop 1
	v_cndmask_b32_e32 v94, v208, v94, vcc
	v_cmp_le_i32_e32 vcc, v204, v209
	s_nop 1
	v_cndmask_b32_e32 v95, v208, v95, vcc
